# D3 state wave hand-scheduled: u first, counted lgkmcnt, two 8-MFMA chains with decay and v_new pack in shadow, state tiles packed under the following chain, decay table in VGPR lanes
# baseline (speedup 1.0000x reference)
; #define LAS __attribute__((address_space(3)))
; #define MFMA32(a, b, c) __builtin_amdgcn_mfma_f32_32x32x16_bf16((a), (b), (c), 0, 0, 0)
; DI float bflo(unsigned u) { return __uint_as_float(u << 16); }
; DI float bfhi(unsigned u) { return __uint_as_float(u & 0xffff0000u); }
; #define D3_BAR() do { asm volatile("s_waitcnt lgkmcnt(0)" ::: "memory"); __builtin_amdgcn_s_barrier(); asm volatile("" ::: "memory"); } while (0)
; DI void d3_block(const Params& P, int bh, int vs, LAS unsigned char* lds, int wave, int lane, int tid) {
;     ...
;         f32x16 S[4]; bf16x8 Sb[8];
; #pragma unroll
;         for (int j = 0; j < 4; ++j)
; #pragma unroll
;             for (int i = 0; i < 16; ++i) S[j][i] = 0.f;
; #pragma unroll
;         for (int G = 0; G < 8; ++G) { Sb[G] = (bf16x8){0, 0, 0, 0, 0, 0, 0, 0}; exSb[G * 64] = Sb[G]; }
;         if (lane == 0) *vflag = 0u;
;         D3_BAR();
;         float gl = GL[0];
; #pragma unroll 1
;         for (int n = 0; n < 128; ++n) {
;             const LAS unsigned char* sb = lds + (n & 1) * D3_SLOT;
;             const LAS bf16x8* fNW = (const LAS bf16x8*)sb + lane; const LAS bf16x8* fKD = (const LAS bf16x8*)(sb + 40960) + lane;
;             const LAS u32x4* fU = (const LAS u32x4*)(sb + 57344) + lane * 2;
;             const float gl_next = GL[(n + 1) & 127];
;             bf16x8 fw[16];
; #pragma unroll
;             for (int q = 0; q < 16; ++q) fw[q] = fNW[q * 64];
;             f32x16 vt[2];
; #pragma unroll
;             for (int t = 0; t < 2; ++t) { const u32x4 a = fU[t * 128], b2 = fU[t * 128 + 1];
;                 vt[t][0] = bflo(a.x); vt[t][1] = bfhi(a.x); vt[t][2] = bflo(a.y); vt[t][3] = bfhi(a.y); vt[t][4] = bflo(a.z); vt[t][5] = bfhi(a.z); vt[t][6] = bflo(a.w); vt[t][7] = bfhi(a.w);
;                 vt[t][8] = bflo(b2.x); vt[t][9] = bfhi(b2.x); vt[t][10] = bflo(b2.y); vt[t][11] = bfhi(b2.y); vt[t][12] = bflo(b2.z); vt[t][13] = bfhi(b2.z); vt[t][14] = bflo(b2.w); vt[t][15] = bfhi(b2.w); }
;             __builtin_amdgcn_sched_barrier(0);
; #pragma unroll
;             for (int G = 0; G < 8; ++G) {
;                 vt[0] = MFMA32(fw[G], Sb[G], vt[0]); vt[1] = MFMA32(fw[8 + G], Sb[G], vt[1]);
;                 if (G < 4) {
; #pragma unroll
;                     for (int i = 0; i < 16; ++i) S[G][i] *= gl; } }
.LBB0_365:
	v_readlane_b32 s0, v254, 13
	v_readlane_b32 s4, v254, 56
	v_readlane_b32 s1, v254, 14
	v_readlane_b32 s5, v254, 57
	s_add_u32 s4, s4, s0
	s_addc_u32 s5, s5, s1
	s_add_u32 s0, s4, 0x2a800000
	s_addc_u32 s1, s5, 0
	v_lshlrev_b32_e32 v186, 2, v240
	s_nop 0
	global_load_dword v224, v186, s[0:1]
	global_load_dword v225, v186, s[0:1] offset:256
	v_mov_b32_e32 v184, v166
	v_mov_b32_e32 v185, 0x25800
	v_mov_b32_e32 v0, 0
	v_mov_b32_e32 v1, v0
	v_mov_b32_e32 v2, v0
	v_mov_b32_e32 v3, v0
	v_mov_b32_e32 v4, v0
	v_mov_b32_e32 v5, v0
	v_mov_b32_e32 v6, v0
	v_mov_b32_e32 v7, v0
	v_mov_b32_e32 v8, v0
	v_mov_b32_e32 v9, v0
	v_mov_b32_e32 v10, v0
	v_mov_b32_e32 v11, v0
	v_mov_b32_e32 v12, v0
	v_mov_b32_e32 v13, v0
	v_mov_b32_e32 v14, v0
	v_mov_b32_e32 v15, v0
	v_mov_b32_e32 v16, v0
	v_mov_b32_e32 v17, v0
	v_mov_b32_e32 v18, v0
	v_mov_b32_e32 v19, v0
	v_mov_b32_e32 v20, v0
	v_mov_b32_e32 v21, v0
	v_mov_b32_e32 v22, v0
	v_mov_b32_e32 v23, v0
	v_mov_b32_e32 v24, v0
	v_mov_b32_e32 v25, v0
	v_mov_b32_e32 v26, v0
	v_mov_b32_e32 v27, v0
	v_mov_b32_e32 v28, v0
	v_mov_b32_e32 v29, v0
	v_mov_b32_e32 v30, v0
	v_mov_b32_e32 v31, v0
	v_mov_b32_e32 v32, v0
	v_mov_b32_e32 v33, v0
	v_mov_b32_e32 v34, v0
	v_mov_b32_e32 v35, v0
	v_mov_b32_e32 v36, v0
	v_mov_b32_e32 v37, v0
	v_mov_b32_e32 v38, v0
	v_mov_b32_e32 v39, v0
	v_mov_b32_e32 v40, v0
	v_mov_b32_e32 v41, v0
	v_mov_b32_e32 v42, v0
	v_mov_b32_e32 v43, v0
	v_mov_b32_e32 v44, v0
	v_mov_b32_e32 v45, v0
	v_mov_b32_e32 v46, v0
	v_mov_b32_e32 v47, v0
	v_mov_b32_e32 v48, v0
	v_mov_b32_e32 v49, v0
	v_mov_b32_e32 v50, v0
	v_mov_b32_e32 v51, v0
	v_mov_b32_e32 v52, v0
	v_mov_b32_e32 v53, v0
	v_mov_b32_e32 v54, v0
	v_mov_b32_e32 v55, v0
	v_mov_b32_e32 v56, v0
	v_mov_b32_e32 v57, v0
	v_mov_b32_e32 v58, v0
	v_mov_b32_e32 v59, v0
	v_mov_b32_e32 v60, v0
	v_mov_b32_e32 v61, v0
	v_mov_b32_e32 v62, v0
	v_mov_b32_e32 v63, v0
	v_mov_b32_e32 v98, v0
	v_mov_b32_e32 v99, v0
	v_mov_b32_e32 v100, v0
	v_mov_b32_e32 v101, v0
	v_mov_b32_e32 v102, v0
	v_mov_b32_e32 v103, v0
	v_mov_b32_e32 v104, v0
	v_mov_b32_e32 v105, v0
	v_mov_b32_e32 v106, v0
	v_mov_b32_e32 v107, v0
	v_mov_b32_e32 v108, v0
	v_mov_b32_e32 v109, v0
	v_mov_b32_e32 v110, v0
	v_mov_b32_e32 v111, v0
	v_mov_b32_e32 v112, v0
	v_mov_b32_e32 v113, v0
	v_mov_b32_e32 v114, v0
	v_mov_b32_e32 v115, v0
	v_mov_b32_e32 v116, v0
	v_mov_b32_e32 v117, v0
	v_mov_b32_e32 v118, v0
	v_mov_b32_e32 v119, v0
	v_mov_b32_e32 v120, v0
	v_mov_b32_e32 v121, v0
	v_mov_b32_e32 v122, v0
	v_mov_b32_e32 v123, v0
	v_mov_b32_e32 v124, v0
	v_mov_b32_e32 v125, v0
	v_mov_b32_e32 v126, v0
	v_mov_b32_e32 v127, v0
	v_mov_b32_e32 v128, v0
	v_mov_b32_e32 v129, v0
	ds_write_b128 v184, v[0:3]
	ds_write_b128 v184, v[0:3] offset:1024
	ds_write_b128 v184, v[0:3] offset:2048
	ds_write_b128 v184, v[0:3] offset:3072
	ds_write_b128 v184, v[0:3] offset:4096
	ds_write_b128 v184, v[0:3] offset:5120
	ds_write_b128 v184, v[0:3] offset:6144
	ds_write_b128 v184, v[0:3] offset:7168
	s_mov_b64 s[4:5], exec
	s_mov_b64 exec, 1
	ds_write_b32 v185, v0
	s_mov_b64 exec, s[4:5]
	s_mov_b32 s8, 0
	s_waitcnt vmcnt(0)
	s_waitcnt lgkmcnt(0)
	s_barrier
.Ld3w0_loop:
	s_and_b32 s5, s8, 63
	s_bitcmp1_b32 s8, 6
	s_nop 2
	v_readlane_b32 s9, v224, s5
	s_cbranch_scc0 .Ld3w0_gl_lo
	v_readlane_b32 s9, v225, s5
.Ld3w0_gl_lo:
	s_bitcmp1_b32 s8, 0
	s_cselect_b32 s4, 0xf000, 0
	s_add_i32 s5, s4, 0xe000
	s_add_i32 s8, s8, 1
	v_lshl_add_u32 v187, v240, 5, s5
	v_lshl_add_u32 v186, v240, 4, s4
	v_mov_b32_e32 v96, s9
	ds_read_b128 v[208:211], v187
	ds_read_b128 v[212:215], v187 offset:16
	ds_read_b128 v[216:219], v187 offset:2048
	ds_read_b128 v[220:223], v187 offset:2064
	ds_read_b128 v[130:133], v186
	ds_read_b128 v[134:137], v186 offset:1024
	ds_read_b128 v[138:141], v186 offset:2048
	ds_read_b128 v[142:145], v186 offset:3072
	ds_read_b128 v[146:149], v186 offset:4096
	ds_read_b128 v[150:153], v186 offset:5120
	ds_read_b128 v[154:157], v186 offset:6144
	ds_read_b128 v[158:161], v186 offset:7168
	ds_read_b128 v[162:165], v186 offset:8192
	ds_read_b128 v[166:169], v186 offset:9216
	ds_read_b128 v[170:173], v186 offset:10240
	s_waitcnt lgkmcnt(11)
	v_lshlrev_b32_e32 v64, 16, v208
	v_and_b32_e32 v65, 0xffff0000, v208
	v_lshlrev_b32_e32 v66, 16, v209
	v_and_b32_e32 v67, 0xffff0000, v209
	v_lshlrev_b32_e32 v68, 16, v210
	v_and_b32_e32 v69, 0xffff0000, v210
	v_lshlrev_b32_e32 v70, 16, v211
	v_and_b32_e32 v71, 0xffff0000, v211
	v_lshlrev_b32_e32 v72, 16, v212
	v_and_b32_e32 v73, 0xffff0000, v212
	v_lshlrev_b32_e32 v74, 16, v213
	v_and_b32_e32 v75, 0xffff0000, v213
	v_lshlrev_b32_e32 v76, 16, v214
	v_and_b32_e32 v77, 0xffff0000, v214
	v_lshlrev_b32_e32 v78, 16, v215
	v_and_b32_e32 v79, 0xffff0000, v215
	v_lshlrev_b32_e32 v80, 16, v216
	v_and_b32_e32 v81, 0xffff0000, v216
	v_lshlrev_b32_e32 v82, 16, v217
	v_and_b32_e32 v83, 0xffff0000, v217
	v_lshlrev_b32_e32 v84, 16, v218
	v_and_b32_e32 v85, 0xffff0000, v218
	v_lshlrev_b32_e32 v86, 16, v219
	v_and_b32_e32 v87, 0xffff0000, v219
	v_lshlrev_b32_e32 v88, 16, v220
	v_and_b32_e32 v89, 0xffff0000, v220
	v_lshlrev_b32_e32 v90, 16, v221
	v_and_b32_e32 v91, 0xffff0000, v221
	v_lshlrev_b32_e32 v92, 16, v222
	v_and_b32_e32 v93, 0xffff0000, v222
	v_lshlrev_b32_e32 v94, 16, v223
	v_and_b32_e32 v95, 0xffff0000, v223
	ds_read_b128 v[174:177], v186 offset:11264
	ds_read_b128 v[178:181], v186 offset:12288
	ds_read_b128 v[196:199], v186 offset:13312
	ds_read_b128 v[200:203], v186 offset:14336
	ds_read_b128 v[204:207], v186 offset:15360
	s_waitcnt lgkmcnt(15)
	s_nop 0
	v_mfma_f32_32x32x16_bf16 v[64:79], v[130:133], v[98:101], v[64:79]
	v_mul_f32_e32 v0, v96, v0
	v_mul_f32_e32 v1, v96, v1
	v_mul_f32_e32 v2, v96, v2
	v_mul_f32_e32 v3, v96, v3
	v_mul_f32_e32 v4, v96, v4
	s_waitcnt lgkmcnt(14)
; #define MFMA32(a, b, c) __builtin_amdgcn_mfma_f32_32x32x16_bf16((a), (b), (c), 0, 0, 0)
; DI void d3_block(const Params& P, int bh, int vs, LAS unsigned char* lds, int wave, int lane, int tid) {
;     ...
; #pragma unroll
;             for (int G = 0; G < 8; ++G) {
;                 vt[0] = MFMA32(fw[G], Sb[G], vt[0]); vt[1] = MFMA32(fw[8 + G], Sb[G], vt[1]);
;                 if (G < 4) {
; #pragma unroll
;                     for (int i = 0; i < 16; ++i) S[G][i] *= gl; } }
;             __builtin_amdgcn_sched_barrier(0);
;             bf16x8 fk[16];
; #pragma unroll
;             for (int q = 0; q < 16; ++q) fk[q] = fKD[q * 64];
;             __builtin_amdgcn_sched_barrier(0);
;             bf16x8 Vb[4];
;             Vb[0] = pack8(vt[0], 0); Vb[1] = pack8(vt[0], 1); Vb[2] = pack8(vt[1], 0); Vb[3] = pack8(vt[1], 1);
	v_mfma_f32_32x32x16_bf16 v[64:79], v[134:137], v[102:105], v[64:79]
	v_mul_f32_e32 v5, v96, v5
	v_mul_f32_e32 v6, v96, v6
	v_mul_f32_e32 v7, v96, v7
	v_mul_f32_e32 v8, v96, v8
	v_mul_f32_e32 v9, v96, v9
	s_waitcnt lgkmcnt(13)
	v_mfma_f32_32x32x16_bf16 v[64:79], v[138:141], v[106:109], v[64:79]
	v_mul_f32_e32 v10, v96, v10
	v_mul_f32_e32 v11, v96, v11
	v_mul_f32_e32 v12, v96, v12
	v_mul_f32_e32 v13, v96, v13
	v_mul_f32_e32 v14, v96, v14
	s_waitcnt lgkmcnt(12)
	v_mfma_f32_32x32x16_bf16 v[64:79], v[142:145], v[110:113], v[64:79]
	v_mul_f32_e32 v15, v96, v15
	v_mul_f32_e32 v16, v96, v16
	v_mul_f32_e32 v17, v96, v17
	v_mul_f32_e32 v18, v96, v18
	v_mul_f32_e32 v19, v96, v19
	s_waitcnt lgkmcnt(11)
	v_mfma_f32_32x32x16_bf16 v[64:79], v[146:149], v[114:117], v[64:79]
	v_mul_f32_e32 v20, v96, v20
	v_mul_f32_e32 v21, v96, v21
	v_mul_f32_e32 v22, v96, v22
	v_mul_f32_e32 v23, v96, v23
	v_mul_f32_e32 v24, v96, v24
	s_waitcnt lgkmcnt(10)
	v_mfma_f32_32x32x16_bf16 v[64:79], v[150:153], v[118:121], v[64:79]
	v_mul_f32_e32 v25, v96, v25
	v_mul_f32_e32 v26, v96, v26
	v_mul_f32_e32 v27, v96, v27
	v_mul_f32_e32 v28, v96, v28
	v_mul_f32_e32 v29, v96, v29
	s_waitcnt lgkmcnt(9)
	v_mfma_f32_32x32x16_bf16 v[64:79], v[154:157], v[122:125], v[64:79]
	v_mul_f32_e32 v30, v96, v30
	v_mul_f32_e32 v31, v96, v31
	v_mul_f32_e32 v32, v96, v32
	v_mul_f32_e32 v33, v96, v33
	v_mul_f32_e32 v34, v96, v34
	s_waitcnt lgkmcnt(8)
	v_mfma_f32_32x32x16_bf16 v[64:79], v[158:161], v[126:129], v[64:79]
	v_mul_f32_e32 v35, v96, v35
	v_mul_f32_e32 v36, v96, v36
	v_mul_f32_e32 v37, v96, v37
	v_mul_f32_e32 v38, v96, v38
	v_mul_f32_e32 v39, v96, v39
	s_waitcnt lgkmcnt(7)
	v_mfma_f32_32x32x16_bf16 v[80:95], v[162:165], v[98:101], v[80:95]
	v_mul_f32_e32 v40, v96, v40
	v_mul_f32_e32 v41, v96, v41
	v_mul_f32_e32 v42, v96, v42
	v_mul_f32_e32 v43, v96, v43
	v_mul_f32_e32 v44, v96, v44
	v_mul_f32_e32 v45, v96, v45
	s_waitcnt lgkmcnt(6)
	v_mfma_f32_32x32x16_bf16 v[80:95], v[166:169], v[102:105], v[80:95]
	v_mul_f32_e32 v46, v96, v46
	v_mul_f32_e32 v47, v96, v47
	v_mul_f32_e32 v48, v96, v48
	v_mul_f32_e32 v49, v96, v49
	v_mul_f32_e32 v50, v96, v50
	v_mul_f32_e32 v51, v96, v51
	s_waitcnt lgkmcnt(5)
	v_mfma_f32_32x32x16_bf16 v[80:95], v[170:173], v[106:109], v[80:95]
	v_mul_f32_e32 v52, v96, v52
	v_mul_f32_e32 v53, v96, v53
	v_mul_f32_e32 v54, v96, v54
	v_mul_f32_e32 v55, v96, v55
	v_mul_f32_e32 v56, v96, v56
	v_mul_f32_e32 v57, v96, v57
	s_waitcnt lgkmcnt(4)
	v_mfma_f32_32x32x16_bf16 v[80:95], v[174:177], v[110:113], v[80:95]
	v_mul_f32_e32 v58, v96, v58
	v_mul_f32_e32 v59, v96, v59
	v_mul_f32_e32 v60, v96, v60
	v_mul_f32_e32 v61, v96, v61
	v_mul_f32_e32 v62, v96, v62
	v_mul_f32_e32 v63, v96, v63
	s_waitcnt lgkmcnt(3)
	v_mfma_f32_32x32x16_bf16 v[80:95], v[178:181], v[114:117], v[80:95]
	v_cvt_pk_bf16_f32 v208, v64, v65
	v_cvt_pk_bf16_f32 v209, v66, v67
	s_waitcnt lgkmcnt(2)
	v_mfma_f32_32x32x16_bf16 v[80:95], v[196:199], v[118:121], v[80:95]
	v_cvt_pk_bf16_f32 v210, v68, v69
	v_cvt_pk_bf16_f32 v211, v70, v71
	s_waitcnt lgkmcnt(1)
	v_mfma_f32_32x32x16_bf16 v[80:95], v[200:203], v[122:125], v[80:95]
	v_cvt_pk_bf16_f32 v212, v72, v73
	v_cvt_pk_bf16_f32 v213, v74, v75
	s_waitcnt lgkmcnt(0)
; #define MFMA32(a, b, c) __builtin_amdgcn_mfma_f32_32x32x16_bf16((a), (b), (c), 0, 0, 0)
; #define D3_BAR() do { asm volatile("s_waitcnt lgkmcnt(0)" ::: "memory"); __builtin_amdgcn_s_barrier(); asm volatile("" ::: "memory"); } while (0)
; DI void d3_block(const Params& P, int bh, int vs, LAS unsigned char* lds, int wave, int lane, int tid) {
;     ...
;             bf16x8 fk[16];
; #pragma unroll
;             for (int q = 0; q < 16; ++q) fk[q] = fKD[q * 64];
;             __builtin_amdgcn_sched_barrier(0);
;             bf16x8 Vb[4];
;             Vb[0] = pack8(vt[0], 0); Vb[1] = pack8(vt[0], 1); Vb[2] = pack8(vt[1], 0); Vb[3] = pack8(vt[1], 1);
; #pragma unroll
;             for (int G = 0; G < 4; ++G) exVb[G * 64] = Vb[G];
;             asm volatile("s_waitcnt lgkmcnt(0)" ::: "memory");
;             if (lane == 0) *vflag = (unsigned)(n + 1);
; #pragma unroll
;             for (int G = 0; G < 4; ++G) { S[0] = MFMA32(fk[G], Vb[G], S[0]); S[1] = MFMA32(fk[4 + G], Vb[G], S[1]); S[2] = MFMA32(fk[8 + G], Vb[G], S[2]); S[3] = MFMA32(fk[12 + G], Vb[G], S[3]); }
;             __builtin_amdgcn_sched_barrier(0);
; #pragma unroll
;             for (int j = 0; j < 4; ++j) { Sb[2 * j] = pack8(S[j], 0); Sb[2 * j + 1] = pack8(S[j], 1); exSb[(2 * j) * 64] = Sb[2 * j]; exSb[(2 * j + 1) * 64] = Sb[2 * j + 1]; }
;             gl = gl_next;
;             D3_BAR();
	v_mfma_f32_32x32x16_bf16 v[80:95], v[204:207], v[126:129], v[80:95]
	v_cvt_pk_bf16_f32 v214, v76, v77
	v_cvt_pk_bf16_f32 v215, v78, v79
	ds_write_b128 v184, v[208:211] offset:8192
	ds_write_b128 v184, v[212:215] offset:9216
	v_add_u32_e32 v186, 0xa000, v186
	ds_read_b128 v[130:133], v186
	ds_read_b128 v[134:137], v186 offset:1024
	ds_read_b128 v[138:141], v186 offset:2048
	ds_read_b128 v[142:145], v186 offset:3072
	ds_read_b128 v[146:149], v186 offset:4096
	ds_read_b128 v[150:153], v186 offset:5120
	ds_read_b128 v[154:157], v186 offset:6144
	ds_read_b128 v[158:161], v186 offset:7168
	ds_read_b128 v[162:165], v186 offset:8192
	ds_read_b128 v[166:169], v186 offset:9216
	ds_read_b128 v[170:173], v186 offset:10240
	ds_read_b128 v[174:177], v186 offset:11264
	ds_read_b128 v[178:181], v186 offset:12288
	ds_read_b128 v[196:199], v186 offset:13312
	ds_read_b128 v[200:203], v186 offset:14336
	ds_read_b128 v[204:207], v186 offset:15360
	v_cvt_pk_bf16_f32 v216, v80, v81
	v_cvt_pk_bf16_f32 v217, v82, v83
	v_cvt_pk_bf16_f32 v218, v84, v85
	v_cvt_pk_bf16_f32 v219, v86, v87
	v_cvt_pk_bf16_f32 v220, v88, v89
	v_cvt_pk_bf16_f32 v221, v90, v91
	v_cvt_pk_bf16_f32 v222, v92, v93
	v_cvt_pk_bf16_f32 v223, v94, v95
	ds_write_b128 v184, v[216:219] offset:10240
	ds_write_b128 v184, v[220:223] offset:11264
	v_mov_b32_e32 v98, s8
	s_waitcnt lgkmcnt(0)
	s_mov_b64 s[4:5], exec
	s_mov_b64 exec, 1
	ds_write_b32 v185, v98
	s_mov_b64 exec, s[4:5]
	v_mfma_f32_32x32x16_bf16 v[0:15], v[130:133], v[208:211], v[0:15]
	v_mfma_f32_32x32x16_bf16 v[0:15], v[134:137], v[212:215], v[0:15]
	v_mfma_f32_32x32x16_bf16 v[0:15], v[138:141], v[216:219], v[0:15]
	v_mfma_f32_32x32x16_bf16 v[0:15], v[142:145], v[220:223], v[0:15]
	v_mfma_f32_32x32x16_bf16 v[16:31], v[146:149], v[208:211], v[16:31]
	s_nop 4
	v_mfma_f32_32x32x16_bf16 v[16:31], v[150:153], v[212:215], v[16:31]
	s_nop 4
	v_mfma_f32_32x32x16_bf16 v[16:31], v[154:157], v[216:219], v[16:31]
	v_cvt_pk_bf16_f32 v98, v0, v1
	v_cvt_pk_bf16_f32 v99, v2, v3
	v_cvt_pk_bf16_f32 v100, v4, v5
	v_cvt_pk_bf16_f32 v101, v6, v7
	v_mfma_f32_32x32x16_bf16 v[16:31], v[158:161], v[220:223], v[16:31]
	v_cvt_pk_bf16_f32 v102, v8, v9
	v_cvt_pk_bf16_f32 v103, v10, v11
	v_cvt_pk_bf16_f32 v104, v12, v13
	v_cvt_pk_bf16_f32 v105, v14, v15
	v_mfma_f32_32x32x16_bf16 v[32:47], v[162:165], v[208:211], v[32:47]
	s_nop 4
	v_mfma_f32_32x32x16_bf16 v[32:47], v[166:169], v[212:215], v[32:47]
	s_nop 4
	v_mfma_f32_32x32x16_bf16 v[32:47], v[170:173], v[216:219], v[32:47]
	v_cvt_pk_bf16_f32 v106, v16, v17
	v_cvt_pk_bf16_f32 v107, v18, v19
	v_cvt_pk_bf16_f32 v108, v20, v21
	v_cvt_pk_bf16_f32 v109, v22, v23
	v_mfma_f32_32x32x16_bf16 v[32:47], v[174:177], v[220:223], v[32:47]
	v_cvt_pk_bf16_f32 v110, v24, v25
	v_cvt_pk_bf16_f32 v111, v26, v27
	v_cvt_pk_bf16_f32 v112, v28, v29
	v_cvt_pk_bf16_f32 v113, v30, v31
	v_mfma_f32_32x32x16_bf16 v[48:63], v[178:181], v[208:211], v[48:63]
	s_nop 4
	v_mfma_f32_32x32x16_bf16 v[48:63], v[196:199], v[212:215], v[48:63]
	s_nop 4
	v_mfma_f32_32x32x16_bf16 v[48:63], v[200:203], v[216:219], v[48:63]
	v_cvt_pk_bf16_f32 v114, v32, v33
	v_cvt_pk_bf16_f32 v115, v34, v35
	v_cvt_pk_bf16_f32 v116, v36, v37
	v_cvt_pk_bf16_f32 v117, v38, v39
	v_mfma_f32_32x32x16_bf16 v[48:63], v[204:207], v[220:223], v[48:63]
	v_cvt_pk_bf16_f32 v118, v40, v41
	v_cvt_pk_bf16_f32 v119, v42, v43
	v_cvt_pk_bf16_f32 v120, v44, v45
	v_cvt_pk_bf16_f32 v121, v46, v47
	ds_write_b128 v184, v[98:101]
	ds_write_b128 v184, v[102:105] offset:1024
	ds_write_b128 v184, v[106:109] offset:2048
	ds_write_b128 v184, v[110:113] offset:3072
	ds_write_b128 v184, v[114:117] offset:4096
	ds_write_b128 v184, v[118:121] offset:5120
	s_nop 5
	v_cvt_pk_bf16_f32 v122, v48, v49
	v_cvt_pk_bf16_f32 v123, v50, v51
	v_cvt_pk_bf16_f32 v124, v52, v53
	v_cvt_pk_bf16_f32 v125, v54, v55
	v_cvt_pk_bf16_f32 v126, v56, v57
	v_cvt_pk_bf16_f32 v127, v58, v59
	v_cvt_pk_bf16_f32 v128, v60, v61
	v_cvt_pk_bf16_f32 v129, v62, v63
	ds_write_b128 v184, v[122:125] offset:6144
	ds_write_b128 v184, v[126:129] offset:7168
	s_waitcnt lgkmcnt(0)
	s_barrier
	s_cmpk_eq_i32 s8, 0x80
	s_cbranch_scc0 .Ld3w0_loop
